# v19 + prologue balance: the f32 row pairs are assigned in reverse wave order, so the waves that convert an extra weight tile do not also get an extra row pair
# speedup vs baseline: 1.0092x; 1.0092x over previous
; __device__ __forceinline__ void p0_prologue(Frame& F0) {
;     ...
;     const int gw = F.bx * NWAVES + F.wave, NGW = F.G * NWAVES, lane = F.lane;
;     p0_weights(F0, (!MK_SPLIT && SPLIT_PROLOGUE) ? 0 : 2, gw, NGW);
;     for (int m0 = 2 * gw; m0 < MP + MS + MMEM; m0 += 2 * NGW) {
;         f32x4 v[2][4];
; #pragma unroll
;         for (int r = 0; r < 2; ++r) {
;             const int m = m0 + r;
;             const float* src = m < MP ? FIN(0) + (size_t)m * D : (m < MP + MS ? FIN(1) + (size_t)(m - MP) * D : FIN(2) + (size_t)(m - MP - MS) * D);
; #pragma unroll
;             for (int jj = 0; jj < 4; ++jj) v[r][jj] = __builtin_nontemporal_load((const f32x4*)src + lane + 64 * jj);
;         }
; #pragma unroll
;         for (int r = 0; r < 2; ++r) {
;             const int m = m0 + r;
;             if (m < MP) {
;                 const float s = p0_row_finish(v[r], ((bf16_t*)(F.ws + WS_XB)) + (size_t)m * D, nullptr, lane);
;                 if (lane < 16) ((float*)(F.ws + WS_RSQ))[(size_t)m * 16 + lane] = lane == 0 ? s : 0.f;
;             } else if (m < MP + MS) {
;                 const int b = m - MP;
;                 const float s = p0_row_finish(v[r], ((bf16_t*)(F.ws + WS_XB)) + (size_t)m * D, ((float*)(F.ws + WS_XS)) + (size_t)b * D, lane);
;                 if (lane < 32) ((float*)(F.ws + WS_SMALL))[b * 32 + lane] = lane == 0 ? s : 0.f;
;             } else {
;                 const int t = m - MP - MS;
;                 const float s = p0_row_finish(v[r], ((bf16_t*)(F.ws + WS_MEMB)) + (size_t)t * D, nullptr, lane);
;                 if (lane == 0) ((float*)(F.ws + WS_SMALL + 65536))[t] = rsqrtf(s * (1.0f / D) + EPS);
.LBB0_242:
	s_sub_i32 s36, 7, s36
	s_sub_i32 s37, 0xff, s37
	s_sub_i32 s38, 0x7ff, s38
	s_cmpk_gt_i32 s38, 0x243f
	s_cbranch_scc1 .LBB0_283
	v_ashrrev_i32_e32 v51, 31, v50
	s_waitcnt vmcnt(28)
	v_lshlrev_b64 v[2:3], 3, v[50:51]
	s_waitcnt vmcnt(26)
	v_lshl_add_u64 v[4:5], s[18:19], 0, v[2:3]
	s_mov_b64 s[4:5], 0x18c00000
	v_lshl_add_u64 v[38:39], v[4:5], 0, s[4:5]
	s_mov_b64 s[4:5], 0x6800000
	s_lshl_b32 s10, s38, 1
	v_lshl_add_u64 v[42:43], v[4:5], 0, s[4:5]
	v_lshl_add_u64 v[4:5], v[50:51], 4, s[18:19]
	s_mov_b64 s[4:5], 0x1b000000
	s_lshl_b32 s12, s37, 9
	s_lshl_b32 s22, s36, 6
	v_lshlrev_b32_e32 v6, 2, v50
	v_lshl_add_u64 v[44:45], v[4:5], 0, s[4:5]
	v_mov_b64_e32 v[4:5], 0x8b00000
	s_lshl_b32 s14, s33, 4
	s_ashr_i32 s11, s10, 31
	s_add_i32 s22, s22, s12
	v_xor_b32_e32 v1, 4, v6
	v_xor_b32_e32 v58, 8, v6
	v_xor_b32_e32 v59, 16, v6
	v_xor_b32_e32 v60, 32, v6
	v_xor_b32_e32 v61, 64, v6
	v_xor_b32_e32 v62, 0x80, v6
	s_waitcnt vmcnt(24)
	v_mov_b64_e32 v[6:7], 0x8b10000
	v_lshl_add_u64 v[46:47], s[18:19], 0, v[4:5]
	s_ashr_i32 s15, s14, 31
	v_add_u32_e32 v4, s22, v50
	s_lshl_b32 s12, s37, 15
	s_lshl_b32 s22, s36, 12
	s_lshl_b64 s[24:25], s[10:11], 6
	s_lshl_b64 s[26:27], s[10:11], 11
	v_lshl_add_u64 v[34:35], s[20:21], 0, 16
	v_lshl_add_u64 v[36:37], s[20:21], 0, 8
	s_mov_b32 s13, 0
	v_cmp_eq_u32_e64 s[8:9], 0, v50
	v_lshl_add_u64 v[40:41], s[18:19], 0, v[6:7]
	v_cmp_gt_i32_e64 s[4:5], 32, v50
	v_cmp_gt_i32_e64 s[6:7], 16, v50
	v_add_u32_e32 v48, 0xfff80000, v4
	s_lshl_b32 s38, s33, 9
	s_add_i32 s22, s12, s22
	s_lshl_b32 s33, s33, 15
	v_lshl_add_u64 v[52:53], v[50:51], 2, s[24:25]
	s_lshl_b64 s[24:25], s[14:15], 6
	v_lshl_add_u64 v[54:55], s[26:27], 0, v[2:3]
	s_lshl_b64 s[26:27], s[14:15], 11
	v_mov_b32_e32 v63, 0x358637bd
	s_mov_b32 s39, 0x800000
	s_mov_b32 s40, 0x6800000
	s_branch .LBB0_246
